# P0 x row loads without nt (stack6 + plain y stores)
# baseline (speedup 1.0000x reference)
.LBB0_91:
	s_add_i32 s20, s3, 0x4000
	s_ashr_i32 s21, s20, 31
	s_cmpk_lt_i32 s20, 0x4000
	s_cselect_b32 s9, s21, 0
	s_cselect_b32 s8, s20, s3
	s_cselect_b32 s10, s45, s47
	s_cselect_b32 s11, s44, s46
	s_lshl_b64 s[8:9], s[8:9], 12
	s_add_u32 s8, s11, s8
	s_addc_u32 s9, s10, s9
	s_waitcnt lgkmcnt(2)
	global_load_dwordx4 v[76:79], v88, s[8:9]
	s_waitcnt lgkmcnt(1)
	global_load_dwordx4 v[72:75], v88, s[8:9] offset:1024
	s_waitcnt lgkmcnt(0)
	global_load_dwordx4 v[68:71], v88, s[8:9] offset:2048
	global_load_dwordx4 v[64:67], v88, s[8:9] offset:3072
	s_add_i32 s8, s74, s3
	s_add_i32 s12, s8, 0x4000
	s_cmpk_lt_i32 s12, 0x4080
	s_cselect_b64 s[18:19], -1, 0
	s_cmpk_gt_i32 s12, 0x407f
	s_waitcnt vmcnt(8)
	v_mov_b32_e32 v60, 0
	v_mov_b32_e32 v61, 0
	v_mov_b32_e32 v62, 0
	v_mov_b32_e32 v63, 0
	v_mov_b32_e32 v52, 0
	v_mov_b32_e32 v53, 0
	v_mov_b32_e32 v54, 0
	v_mov_b32_e32 v55, 0
	v_mov_b32_e32 v44, 0
	v_mov_b32_e32 v45, 0
	v_mov_b32_e32 v46, 0
	v_mov_b32_e32 v47, 0
	v_mov_b32_e32 v32, 0
	v_mov_b32_e32 v33, 0
	v_mov_b32_e32 v34, 0
	v_mov_b32_e32 v35, 0
	s_cbranch_scc1 .LBB0_93
	s_ashr_i32 s9, s12, 31
	s_cmpk_lt_i32 s12, 0x4000
	s_cselect_b32 s9, s9, 0
	s_cselect_b32 s8, s12, s8
	s_cselect_b32 s10, s45, s47
	s_cselect_b32 s11, s44, s46
	s_lshl_b64 s[8:9], s[8:9], 12
	s_add_u32 s8, s11, s8
	s_addc_u32 s9, s10, s9
	global_load_dwordx4 v[60:63], v88, s[8:9]
	global_load_dwordx4 v[52:55], v88, s[8:9] offset:1024
	global_load_dwordx4 v[44:47], v88, s[8:9] offset:2048
	global_load_dwordx4 v[32:35], v88, s[8:9] offset:3072
.LBB0_93:
	s_add_i32 s8, s23, s3
	s_add_i32 s10, s8, 0x4000
	s_cmpk_lt_i32 s10, 0x4080
	v_mov_b32_e32 v16, 0
	s_cselect_b64 s[16:17], -1, 0
	s_cmpk_gt_i32 s10, 0x407f
	v_mov_b32_e32 v56, 0
	v_mov_b32_e32 v57, 0
	v_mov_b32_e32 v58, 0
	v_mov_b32_e32 v59, 0
	v_mov_b32_e32 v48, 0
	v_mov_b32_e32 v49, 0
	v_mov_b32_e32 v50, 0
	v_mov_b32_e32 v51, 0
	v_mov_b32_e32 v36, 0
	v_mov_b32_e32 v37, 0
	v_mov_b32_e32 v38, 0
	v_mov_b32_e32 v39, 0
	v_mov_b32_e32 v24, 0
	v_mov_b32_e32 v25, 0
	v_mov_b32_e32 v26, 0
	v_mov_b32_e32 v27, 0
	s_cbranch_scc1 .LBB0_95
	s_ashr_i32 s9, s10, 31
	s_cmpk_lt_i32 s10, 0x4000
	s_cselect_b32 s9, s9, 0
	s_cselect_b32 s8, s10, s8
	s_cselect_b32 s11, s45, s47
	s_cselect_b32 s13, s44, s46
	s_lshl_b64 s[8:9], s[8:9], 12
	s_add_u32 s8, s13, s8
	s_addc_u32 s9, s11, s9
	global_load_dwordx4 v[56:59], v88, s[8:9]
	global_load_dwordx4 v[48:51], v88, s[8:9] offset:1024
	global_load_dwordx4 v[36:39], v88, s[8:9] offset:2048
	global_load_dwordx4 v[24:27], v88, s[8:9] offset:3072
.LBB0_95:
	s_add_i32 s9, s24, s3
	s_add_i32 s8, s9, 0x4000
	s_cmpk_lt_i32 s8, 0x4080
	s_cselect_b64 s[14:15], -1, 0
	s_cmpk_gt_i32 s8, 0x407f
	v_mov_b32_e32 v17, 0
	v_mov_b32_e32 v18, 0
	v_mov_b32_e32 v19, 0
	v_mov_b32_e32 v40, 0
	v_mov_b32_e32 v41, 0
	v_mov_b32_e32 v42, 0
	v_mov_b32_e32 v43, 0
	v_mov_b32_e32 v28, 0
	v_mov_b32_e32 v29, 0
	v_mov_b32_e32 v30, 0
	v_mov_b32_e32 v31, 0
	v_mov_b32_e32 v20, 0
	v_mov_b32_e32 v21, 0
	v_mov_b32_e32 v22, 0
	v_mov_b32_e32 v23, 0
	s_cbranch_scc1 .LBB0_97
	s_ashr_i32 s11, s8, 31
	s_cmpk_lt_i32 s8, 0x4000
	s_cselect_b32 s27, s11, 0
	s_cselect_b32 s26, s8, s9
	s_cselect_b32 s9, s45, s47
	s_cselect_b32 s11, s44, s46
	s_lshl_b64 s[26:27], s[26:27], 12
	s_add_u32 s26, s11, s26
	s_addc_u32 s27, s9, s27
	global_load_dwordx4 v[16:19], v88, s[26:27]
	global_load_dwordx4 v[40:43], v88, s[26:27] offset:1024
	global_load_dwordx4 v[28:31], v88, s[26:27] offset:2048
	global_load_dwordx4 v[20:23], v88, s[26:27] offset:3072
